# static s_setprio 1 for waves 0-3 (other half) around the K-loops of phases 3, 10, 12, 13; flips deleted
# baseline (speedup 1.0000x reference)
;     __device__ __forceinline__ bool next(int i, Unit& u) const { if (i != 0 || c >= n) return false; u.pm = 0; u.pn = c; u.kt0 = 0; u.nkt = ntk; u.piece = -1; return true; }
; template <class Epi, class Sched>
; __device__ __forceinline__ void gemm_phase(LAS unsigned char* lds, const Gemm g, const Sched& S, const Epi& E) {
;     ...
;         const bool has_next = S.next(ui + 1, nxt);
;         const char* nA = has_next ? (const char*)g.A + (size_t)nxt.pm * tstepA + (size_t)nxt.pn * g.a_pn_off + (size_t)nxt.kt0 * kstep : cA; const char* nB = has_next ? (const char*)g.Bt + (size_t)nxt.pn * tstepB + (size_t)nxt.kt0 * kstep : cB;
;     ...
;         for (int a = 0; a < 2; ++a)
; #pragma unroll
;             for (int b = 0; b < 2; ++b)
; #pragma unroll
;                 for (int m = 0; m < 4; ++m)
; #pragma unroll
;                     for (int n = 0; n < 2; ++n) acc[a][b][m][n] = (f32x4){0.f, 0.f, 0.f, 0.f};
;         cur = nxt; cA = nA; cB = nB; ++ui;
.LBB0_474:
	s_ashr_i32 s17, s16, 31
	v_cmp_lt_i64_e32 vcc, s[18:19], v[140:141]
	s_lshl_b64 s[18:19], s[16:17], 20
	s_add_u32 s18, s28, s18
	s_addc_u32 s19, s29, s19
	s_and_b64 s[20:21], vcc, exec
	s_cselect_b32 s17, s19, s23
	s_cselect_b32 s45, s18, s22
	s_ashr_i32 s15, s14, 31
	s_lshl_b64 s[20:21], s[14:15], 20
	s_add_u32 s20, s84, s20
	s_addc_u32 s21, s85, s21
	s_and_b64 s[26:27], vcc, exec
	s_cselect_b32 s15, s21, s25
	s_cselect_b32 s46, s20, s24
	s_add_u32 s22, s22, 0x80080
	s_addc_u32 s23, s23, 0
	s_add_u32 s47, s24, 0x100
	v_mov_b32_e32 v0, 0
	s_addc_u32 s48, s25, 0
	s_mov_b32 s49, -2
	v_mov_b32_e32 v1, v0
	v_mov_b32_e32 v2, v0
	v_mov_b32_e32 v3, v0
	v_mov_b32_e32 v4, v0
	v_mov_b32_e32 v5, v0
	v_mov_b32_e32 v6, v0
	v_mov_b32_e32 v7, v0
	v_mov_b32_e32 v8, v0
	v_mov_b32_e32 v9, v0
	v_mov_b32_e32 v10, v0
	v_mov_b32_e32 v11, v0
	v_mov_b32_e32 v12, v0
	v_mov_b32_e32 v13, v0
	v_mov_b32_e32 v14, v0
	v_mov_b32_e32 v15, v0
	v_mov_b32_e32 v24, v0
	v_mov_b32_e32 v25, v0
	v_mov_b32_e32 v26, v0
	v_mov_b32_e32 v27, v0
	v_mov_b32_e32 v28, v0
	v_mov_b32_e32 v29, v0
	v_mov_b32_e32 v30, v0
	v_mov_b32_e32 v31, v0
	v_mov_b32_e32 v40, v0
	v_mov_b32_e32 v41, v0
	v_mov_b32_e32 v42, v0
	v_mov_b32_e32 v43, v0
	v_mov_b32_e32 v44, v0
	v_mov_b32_e32 v45, v0
	v_mov_b32_e32 v46, v0
	v_mov_b32_e32 v47, v0
	v_mov_b32_e32 v16, v0
	v_mov_b32_e32 v17, v0
	v_mov_b32_e32 v18, v0
	v_mov_b32_e32 v19, v0
	v_mov_b32_e32 v20, v0
	v_mov_b32_e32 v21, v0
	v_mov_b32_e32 v22, v0
	v_mov_b32_e32 v23, v0
	v_mov_b32_e32 v32, v0
	v_mov_b32_e32 v33, v0
	v_mov_b32_e32 v34, v0
	v_mov_b32_e32 v35, v0
	v_mov_b32_e32 v36, v0
	v_mov_b32_e32 v37, v0
	v_mov_b32_e32 v38, v0
	v_mov_b32_e32 v39, v0
	v_mov_b32_e32 v48, v0
	v_mov_b32_e32 v49, v0
	v_mov_b32_e32 v50, v0
	v_mov_b32_e32 v51, v0
	v_mov_b32_e32 v52, v0
	v_mov_b32_e32 v53, v0
	v_mov_b32_e32 v54, v0
	v_mov_b32_e32 v55, v0
	v_mov_b32_e32 v56, v0
	v_mov_b32_e32 v57, v0
	v_mov_b32_e32 v58, v0
	v_mov_b32_e32 v59, v0
	v_mov_b32_e32 v60, v0
	v_mov_b32_e32 v61, v0
	v_mov_b32_e32 v62, v0
	v_mov_b32_e32 v63, v0
	v_mov_b32_e32 v64, v0
	v_mov_b32_e32 v65, v0
	v_mov_b32_e32 v66, v0
	v_mov_b32_e32 v67, v0
	v_mov_b32_e32 v68, v0
	v_mov_b32_e32 v69, v0
	v_mov_b32_e32 v70, v0
	v_mov_b32_e32 v71, v0
	v_mov_b32_e32 v72, v0
	v_mov_b32_e32 v73, v0
	v_mov_b32_e32 v74, v0
	v_mov_b32_e32 v75, v0
	v_mov_b32_e32 v76, v0
	v_mov_b32_e32 v77, v0
	v_mov_b32_e32 v78, v0
	v_mov_b32_e32 v79, v0
	v_mov_b32_e32 v88, v0
	v_mov_b32_e32 v89, v0
	v_mov_b32_e32 v90, v0
	v_mov_b32_e32 v91, v0
	v_mov_b32_e32 v92, v0
	v_mov_b32_e32 v93, v0
	v_mov_b32_e32 v94, v0
	v_mov_b32_e32 v95, v0
	v_mov_b32_e32 v104, v0
	v_mov_b32_e32 v105, v0
	v_mov_b32_e32 v106, v0
	v_mov_b32_e32 v107, v0
	v_mov_b32_e32 v108, v0
	v_mov_b32_e32 v109, v0
	v_mov_b32_e32 v110, v0
	v_mov_b32_e32 v111, v0
	v_mov_b32_e32 v80, v0
	v_mov_b32_e32 v81, v0
	v_mov_b32_e32 v82, v0
	v_mov_b32_e32 v83, v0
	v_mov_b32_e32 v84, v0
	v_mov_b32_e32 v85, v0
	v_mov_b32_e32 v86, v0
	v_mov_b32_e32 v87, v0
	v_mov_b32_e32 v96, v0
	v_mov_b32_e32 v97, v0
	v_mov_b32_e32 v98, v0
	v_mov_b32_e32 v99, v0
	v_mov_b32_e32 v100, v0
	v_mov_b32_e32 v101, v0
	v_mov_b32_e32 v102, v0
	v_mov_b32_e32 v103, v0
	v_mov_b32_e32 v112, v0
	v_mov_b32_e32 v113, v0
	v_mov_b32_e32 v114, v0
	v_mov_b32_e32 v115, v0
	v_mov_b32_e32 v116, v0
	v_mov_b32_e32 v117, v0
	v_mov_b32_e32 v118, v0
	v_mov_b32_e32 v119, v0
	v_mov_b32_e32 v120, v0
	v_mov_b32_e32 v121, v0
	v_mov_b32_e32 v122, v0
	v_mov_b32_e32 v123, v0
	v_mov_b32_e32 v124, v0
	v_mov_b32_e32 v125, v0
	v_mov_b32_e32 v126, v0
	v_mov_b32_e32 v127, v0
	s_lshr_b32 s57, s3, 8
	s_cmp_lg_u32 s57, 0
	s_cbranch_scc1 .Lprio_475
	s_setprio 1

; template <class Epi, class Sched>
; __device__ __forceinline__ void gemm_phase(LAS unsigned char* lds, const Gemm g, const Sched& S, const Epi& E) {
;     ...
;         for (int a = 0; a < 2; ++a)
; #pragma unroll
;             for (int b = 0; b < 2; ++b)
; #pragma unroll
;                 for (int m = 0; m < 4; ++m)
; #pragma unroll
;                     for (int n = 0; n < 2; ++n) acc[a][b][m][n] = (f32x4){0.f, 0.f, 0.f, 0.f};
;         cur = nxt; cA = nA; cB = nB; ++ui;
.LBB0_1652:
	s_mov_b32 s80, s79
	s_add_i32 s65, s65, 1
	s_mov_b32 s68, s12
	s_mul_i32 s12, s65, s96
	s_add_i32 s35, s12, s2
	s_bfe_u32 s79, s35, 0x40003
	s_lshl_b32 s79, s79, 8
	s_cmpk_lt_u32 s35, 0x100
	s_cselect_b32 s79, s79, 0
	s_mov_b32 s69, s14
	s_max_i32 s14, s35, 0x100
	s_and_b32 s66, s14, 7
	s_lshl_b32 s15, s66, 9
	s_cmpk_lt_i32 s35, 0x100
	s_cselect_b64 s[12:13], -1, 0
	s_and_b64 s[12:13], s[12:13], exec
	s_cselect_b32 s12, s35, 0
	s_cselect_b32 s70, 0, s15
	s_ashr_i32 s13, s12, 31
	s_lshr_b32 s13, s13, 29
	s_add_i32 s13, s12, s13
	s_ashr_i32 s15, s13, 3
	s_and_b32 s13, s13, 0x7fffff8
	s_sub_i32 s12, s12, s13
	s_lshl_b32 s12, s12, 5
	s_add_i32 s12, s12, s15
	s_ashr_i32 s13, s12, 31
	s_lshr_b32 s13, s13, 26
	s_add_i32 s15, s12, s13
	s_and_b32 s13, s15, 0xffffffc0
	s_mov_b64 s[36:37], s[18:19]
	s_sub_i32 s18, s12, s13
	s_bfe_i32 s12, s18, 0x80000
	s_bfe_u32 s12, s12, 0x3000c
	s_add_i32 s19, s18, s12
	s_bfe_i32 s12, s19, 0x80000
	s_sext_i32_i16 s12, s12
	s_mov_b64 s[6:7], s[20:21]
	s_ashr_i32 s20, s12, 3
	s_bfe_u32 s21, s14, 0x30003
	s_cmpk_lt_i32 s35, 0x100
	s_cselect_b64 s[12:13], -1, 0
	s_and_b64 s[12:13], s[12:13], exec
	s_cselect_b32 s12, s20, s21
	s_ashr_i32 s13, s15, 6
	s_and_b32 s15, s19, 0xf8
	s_sub_i32 s15, s18, s15
	s_addk_i32 s14, 0xff00
	s_lshl_b32 s13, s13, 3
	s_sext_i32_i8 s15, s15
	s_lshr_b32 s14, s14, 6
	s_add_i32 s13, s13, s15
	s_add_i32 s18, s14, 32
	s_cmpk_lt_i32 s35, 0x100
	s_cselect_b64 s[28:29], -1, 0
	s_and_b64 s[14:15], s[28:29], exec
	s_cselect_b32 s14, s13, s18
	s_cmpk_gt_i32 s35, 0x17f
	s_cselect_b64 s[30:31], -1, 0
	s_ashr_i32 s15, s14, 31
	s_lshl_b64 s[18:19], s[14:15], 20
	s_add_u32 s13, s38, s18
	s_addc_u32 s15, s39, s19
	s_add_u32 s20, s13, s70
	s_addc_u32 s21, s15, 0
	s_ashr_i32 s13, s12, 31
	s_lshl_b64 s[18:19], s[12:13], 20
	s_add_u32 s13, s40, s18
	s_addc_u32 s15, s41, s19
	s_add_u32 s18, s13, s70
	s_addc_u32 s19, s15, 0
	s_cmpk_lt_i32 s35, 0x180
	s_cselect_b32 s13, s21, s7
	s_cselect_b32 s15, s20, s6
	s_cselect_b32 s70, s19, s37
	s_cselect_b32 s71, s18, s36
	s_add_i32 s72, s67, -2
	s_add_u32 s6, s6, 0x80080
	s_addc_u32 s7, s7, 0
	s_add_u32 s73, s36, 0x100
	v_mov_b32_e32 v0, 0
	s_mov_b32 s34, 0
	s_addc_u32 s74, s37, 0
	v_mov_b32_e32 v1, v0
	v_mov_b32_e32 v2, v0
	v_mov_b32_e32 v3, v0
	v_mov_b32_e32 v4, v0
	v_mov_b32_e32 v5, v0
	v_mov_b32_e32 v6, v0
	v_mov_b32_e32 v7, v0
	v_mov_b32_e32 v8, v0
	v_mov_b32_e32 v9, v0
	v_mov_b32_e32 v10, v0
	v_mov_b32_e32 v11, v0
	v_mov_b32_e32 v12, v0
	v_mov_b32_e32 v13, v0
	v_mov_b32_e32 v14, v0
	v_mov_b32_e32 v15, v0
	v_mov_b32_e32 v20, v0
	v_mov_b32_e32 v21, v0
	v_mov_b32_e32 v22, v0
	v_mov_b32_e32 v23, v0
	v_mov_b32_e32 v28, v0
	v_mov_b32_e32 v29, v0
	v_mov_b32_e32 v30, v0
	v_mov_b32_e32 v31, v0
	v_mov_b32_e32 v36, v0
	v_mov_b32_e32 v37, v0
	v_mov_b32_e32 v38, v0
	v_mov_b32_e32 v39, v0
	v_mov_b32_e32 v44, v0
	v_mov_b32_e32 v45, v0
	v_mov_b32_e32 v46, v0
	v_mov_b32_e32 v47, v0
	v_mov_b32_e32 v16, v0
	v_mov_b32_e32 v17, v0
	v_mov_b32_e32 v18, v0
	v_mov_b32_e32 v19, v0
	v_mov_b32_e32 v24, v0
	v_mov_b32_e32 v25, v0
	v_mov_b32_e32 v26, v0
	v_mov_b32_e32 v27, v0
	v_mov_b32_e32 v32, v0
	v_mov_b32_e32 v33, v0
	v_mov_b32_e32 v34, v0
	v_mov_b32_e32 v35, v0
	v_mov_b32_e32 v40, v0
	v_mov_b32_e32 v41, v0
	v_mov_b32_e32 v42, v0
	v_mov_b32_e32 v43, v0
	v_mov_b32_e32 v48, v0
	v_mov_b32_e32 v49, v0
	v_mov_b32_e32 v50, v0
	v_mov_b32_e32 v51, v0
	v_mov_b32_e32 v52, v0
	v_mov_b32_e32 v53, v0
	v_mov_b32_e32 v54, v0
	v_mov_b32_e32 v55, v0
	v_mov_b32_e32 v56, v0
	v_mov_b32_e32 v57, v0
	v_mov_b32_e32 v58, v0
	v_mov_b32_e32 v59, v0
	v_mov_b32_e32 v60, v0
	v_mov_b32_e32 v61, v0
	v_mov_b32_e32 v62, v0
	v_mov_b32_e32 v63, v0
	v_mov_b32_e32 v64, v0
	v_mov_b32_e32 v65, v0
	v_mov_b32_e32 v66, v0
	v_mov_b32_e32 v67, v0
	v_mov_b32_e32 v68, v0
	v_mov_b32_e32 v69, v0
	v_mov_b32_e32 v70, v0
	v_mov_b32_e32 v71, v0
	v_mov_b32_e32 v72, v0
	v_mov_b32_e32 v73, v0
	v_mov_b32_e32 v74, v0
	v_mov_b32_e32 v75, v0
	v_mov_b32_e32 v76, v0
	v_mov_b32_e32 v77, v0
	v_mov_b32_e32 v78, v0
	v_mov_b32_e32 v79, v0
	v_mov_b32_e32 v84, v0
	v_mov_b32_e32 v85, v0
	v_mov_b32_e32 v86, v0
	v_mov_b32_e32 v87, v0
	v_mov_b32_e32 v92, v0
	v_mov_b32_e32 v93, v0
	v_mov_b32_e32 v94, v0
	v_mov_b32_e32 v95, v0
	v_mov_b32_e32 v100, v0
	v_mov_b32_e32 v101, v0
	v_mov_b32_e32 v102, v0
	v_mov_b32_e32 v103, v0
	v_mov_b32_e32 v108, v0
	v_mov_b32_e32 v109, v0
	v_mov_b32_e32 v110, v0
	v_mov_b32_e32 v111, v0
	v_mov_b32_e32 v80, v0
	v_mov_b32_e32 v81, v0
	v_mov_b32_e32 v82, v0
	v_mov_b32_e32 v83, v0
	v_mov_b32_e32 v88, v0
	v_mov_b32_e32 v89, v0
	v_mov_b32_e32 v90, v0
	v_mov_b32_e32 v91, v0
	v_mov_b32_e32 v96, v0
	v_mov_b32_e32 v97, v0
	v_mov_b32_e32 v98, v0
	v_mov_b32_e32 v99, v0
	v_mov_b32_e32 v104, v0
	v_mov_b32_e32 v105, v0
	v_mov_b32_e32 v106, v0
	v_mov_b32_e32 v107, v0
	v_mov_b32_e32 v112, v0
	v_mov_b32_e32 v113, v0
	v_mov_b32_e32 v114, v0
	v_mov_b32_e32 v115, v0
	v_mov_b32_e32 v116, v0
	v_mov_b32_e32 v117, v0
	v_mov_b32_e32 v118, v0
	v_mov_b32_e32 v119, v0
	v_mov_b32_e32 v120, v0
	v_mov_b32_e32 v121, v0
	v_mov_b32_e32 v122, v0
	v_mov_b32_e32 v123, v0
	v_mov_b32_e32 v124, v0
	v_mov_b32_e32 v125, v0
	v_mov_b32_e32 v126, v0
	v_mov_b32_e32 v127, v0
	s_lshr_b32 s92, s3, 8
	s_cmp_lg_u32 s92, 0
	s_cbranch_scc1 .Lprio_1653
	s_setprio 1

;     __device__ __forceinline__ bool next(int i, Unit& u) const { if (i != 0 || c >= n) return false; u.pm = 0; u.pn = c; u.kt0 = 0; u.nkt = ntk; u.piece = -1; return true; }
; template <class Epi, class Sched>
; __device__ __forceinline__ void gemm_phase(LAS unsigned char* lds, const Gemm g, const Sched& S, const Epi& E) {
;     ...
;         const bool has_next = S.next(ui + 1, nxt);
;         const char* nA = has_next ? (const char*)g.A + (size_t)nxt.pm * tstepA + (size_t)nxt.pn * g.a_pn_off + (size_t)nxt.kt0 * kstep : cA; const char* nB = has_next ? (const char*)g.Bt + (size_t)nxt.pn * tstepB + (size_t)nxt.kt0 * kstep : cB;
;     ...
;         for (int a = 0; a < 2; ++a)
; #pragma unroll
;             for (int b = 0; b < 2; ++b)
; #pragma unroll
;                 for (int m = 0; m < 4; ++m)
; #pragma unroll
;                     for (int n = 0; n < 2; ++n) acc[a][b][m][n] = (f32x4){0.f, 0.f, 0.f, 0.f};
;         cur = nxt; cA = nA; cB = nB; ++ui;
.LBB0_1842:
	s_ashr_i32 s15, s14, 31
	v_cmp_lt_i64_e32 vcc, s[16:17], v[140:141]
	s_lshl_b64 s[16:17], s[14:15], 20
	s_add_u32 s16, s28, s16
	s_addc_u32 s17, s29, s17
	s_and_b64 s[18:19], vcc, exec
	s_cselect_b32 s15, s17, s23
	s_cselect_b32 s48, s16, s22
	s_ashr_i32 s13, s12, 31
	s_lshl_b64 s[18:19], s[12:13], 20
	s_add_u32 s18, s30, s18
	s_addc_u32 s19, s31, s19
	s_and_b64 s[26:27], vcc, exec
	s_cselect_b32 s13, s19, s25
	s_cselect_b32 s49, s18, s24
	s_add_u32 s22, s22, 0x80080
	s_addc_u32 s23, s23, 0
	s_add_u32 s50, s24, 0x100
	v_mov_b32_e32 v0, 0
	s_addc_u32 s51, s25, 0
	s_mov_b32 s52, -2
	v_mov_b32_e32 v1, v0
	v_mov_b32_e32 v2, v0
	v_mov_b32_e32 v3, v0
	v_mov_b32_e32 v8, v0
	v_mov_b32_e32 v9, v0
	v_mov_b32_e32 v10, v0
	v_mov_b32_e32 v11, v0
	v_mov_b32_e32 v16, v0
	v_mov_b32_e32 v17, v0
	v_mov_b32_e32 v18, v0
	v_mov_b32_e32 v19, v0
	v_mov_b32_e32 v24, v0
	v_mov_b32_e32 v25, v0
	v_mov_b32_e32 v26, v0
	v_mov_b32_e32 v27, v0
	v_mov_b32_e32 v32, v0
	v_mov_b32_e32 v33, v0
	v_mov_b32_e32 v34, v0
	v_mov_b32_e32 v35, v0
	v_mov_b32_e32 v40, v0
	v_mov_b32_e32 v41, v0
	v_mov_b32_e32 v42, v0
	v_mov_b32_e32 v43, v0
	v_mov_b32_e32 v48, v0
	v_mov_b32_e32 v49, v0
	v_mov_b32_e32 v50, v0
	v_mov_b32_e32 v51, v0
	v_mov_b32_e32 v56, v0
	v_mov_b32_e32 v57, v0
	v_mov_b32_e32 v58, v0
	v_mov_b32_e32 v59, v0
	v_mov_b32_e32 v4, v0
	v_mov_b32_e32 v5, v0
	v_mov_b32_e32 v6, v0
	v_mov_b32_e32 v7, v0
	v_mov_b32_e32 v12, v0
	v_mov_b32_e32 v13, v0
	v_mov_b32_e32 v14, v0
	v_mov_b32_e32 v15, v0
	v_mov_b32_e32 v20, v0
	v_mov_b32_e32 v21, v0
	v_mov_b32_e32 v22, v0
	v_mov_b32_e32 v23, v0
	v_mov_b32_e32 v28, v0
	v_mov_b32_e32 v29, v0
	v_mov_b32_e32 v30, v0
	v_mov_b32_e32 v31, v0
	v_mov_b32_e32 v36, v0
	v_mov_b32_e32 v37, v0
	v_mov_b32_e32 v38, v0
	v_mov_b32_e32 v39, v0
	v_mov_b32_e32 v44, v0
	v_mov_b32_e32 v45, v0
	v_mov_b32_e32 v46, v0
	v_mov_b32_e32 v47, v0
	v_mov_b32_e32 v52, v0
	v_mov_b32_e32 v53, v0
	v_mov_b32_e32 v54, v0
	v_mov_b32_e32 v55, v0
	v_mov_b32_e32 v60, v0
	v_mov_b32_e32 v61, v0
	v_mov_b32_e32 v62, v0
	v_mov_b32_e32 v63, v0
	v_mov_b32_e32 v64, v0
	v_mov_b32_e32 v65, v0
	v_mov_b32_e32 v66, v0
	v_mov_b32_e32 v67, v0
	v_mov_b32_e32 v72, v0
	v_mov_b32_e32 v73, v0
	v_mov_b32_e32 v74, v0
	v_mov_b32_e32 v75, v0
	v_mov_b32_e32 v80, v0
	v_mov_b32_e32 v81, v0
	v_mov_b32_e32 v82, v0
	v_mov_b32_e32 v83, v0
	v_mov_b32_e32 v88, v0
	v_mov_b32_e32 v89, v0
	v_mov_b32_e32 v90, v0
	v_mov_b32_e32 v91, v0
	v_mov_b32_e32 v96, v0
	v_mov_b32_e32 v97, v0
	v_mov_b32_e32 v98, v0
	v_mov_b32_e32 v99, v0
	v_mov_b32_e32 v104, v0
	v_mov_b32_e32 v105, v0
	v_mov_b32_e32 v106, v0
	v_mov_b32_e32 v107, v0
	v_mov_b32_e32 v112, v0
	v_mov_b32_e32 v113, v0
	v_mov_b32_e32 v114, v0
	v_mov_b32_e32 v115, v0
	v_mov_b32_e32 v120, v0
	v_mov_b32_e32 v121, v0
	v_mov_b32_e32 v122, v0
	v_mov_b32_e32 v123, v0
	v_mov_b32_e32 v68, v0
	v_mov_b32_e32 v69, v0
	v_mov_b32_e32 v70, v0
	v_mov_b32_e32 v71, v0
	v_mov_b32_e32 v76, v0
	v_mov_b32_e32 v77, v0
	v_mov_b32_e32 v78, v0
	v_mov_b32_e32 v79, v0
	v_mov_b32_e32 v84, v0
	v_mov_b32_e32 v85, v0
	v_mov_b32_e32 v86, v0
	v_mov_b32_e32 v87, v0
	v_mov_b32_e32 v92, v0
	v_mov_b32_e32 v93, v0
	v_mov_b32_e32 v94, v0
	v_mov_b32_e32 v95, v0
	v_mov_b32_e32 v100, v0
	v_mov_b32_e32 v101, v0
	v_mov_b32_e32 v102, v0
	v_mov_b32_e32 v103, v0
	v_mov_b32_e32 v108, v0
	v_mov_b32_e32 v109, v0
	v_mov_b32_e32 v110, v0
	v_mov_b32_e32 v111, v0
	v_mov_b32_e32 v116, v0
	v_mov_b32_e32 v117, v0
	v_mov_b32_e32 v118, v0
	v_mov_b32_e32 v119, v0
	v_mov_b32_e32 v124, v0
	v_mov_b32_e32 v125, v0
	v_mov_b32_e32 v126, v0
	v_mov_b32_e32 v127, v0
	s_lshr_b32 s57, s3, 8
	s_cmp_lg_u32 s57, 0
	s_cbranch_scc1 .Lprio_1843
	s_setprio 1

; template <class Epi, class Sched>
; __device__ __forceinline__ void gemm_phase(LAS unsigned char* lds, const Gemm g, const Sched& S, const Epi& E) {
;     ...
;         for (int a = 0; a < 2; ++a)
; #pragma unroll
;             for (int b = 0; b < 2; ++b)
; #pragma unroll
;                 for (int m = 0; m < 4; ++m)
; #pragma unroll
;                     for (int n = 0; n < 2; ++n) acc[a][b][m][n] = (f32x4){0.f, 0.f, 0.f, 0.f};
;         cur = nxt; cA = nA; cB = nB; ++ui;
.LBB0_1914:
	s_add_i32 s28, s66, -2
	s_add_u32 s6, s6, 0x160080
	s_addc_u32 s7, s7, 0
	s_add_u32 s29, s24, 0x100
	v_mov_b32_e32 v0, 0
	s_addc_u32 s67, s25, 0
	s_mov_b32 s24, 0
	v_mov_b32_e32 v1, v0
	v_mov_b32_e32 v2, v0
	v_mov_b32_e32 v3, v0
	v_mov_b32_e32 v4, v0
	v_mov_b32_e32 v5, v0
	v_mov_b32_e32 v6, v0
	v_mov_b32_e32 v7, v0
	v_mov_b32_e32 v8, v0
	v_mov_b32_e32 v9, v0
	v_mov_b32_e32 v10, v0
	v_mov_b32_e32 v11, v0
	v_mov_b32_e32 v12, v0
	v_mov_b32_e32 v13, v0
	v_mov_b32_e32 v14, v0
	v_mov_b32_e32 v15, v0
	v_mov_b32_e32 v20, v0
	v_mov_b32_e32 v21, v0
	v_mov_b32_e32 v22, v0
	v_mov_b32_e32 v23, v0
	v_mov_b32_e32 v28, v0
	v_mov_b32_e32 v29, v0
	v_mov_b32_e32 v30, v0
	v_mov_b32_e32 v31, v0
	v_mov_b32_e32 v36, v0
	v_mov_b32_e32 v37, v0
	v_mov_b32_e32 v38, v0
	v_mov_b32_e32 v39, v0
	v_mov_b32_e32 v44, v0
	v_mov_b32_e32 v45, v0
	v_mov_b32_e32 v46, v0
	v_mov_b32_e32 v47, v0
	v_mov_b32_e32 v16, v0
	v_mov_b32_e32 v17, v0
	v_mov_b32_e32 v18, v0
	v_mov_b32_e32 v19, v0
	v_mov_b32_e32 v24, v0
	v_mov_b32_e32 v25, v0
	v_mov_b32_e32 v26, v0
	v_mov_b32_e32 v27, v0
	v_mov_b32_e32 v32, v0
	v_mov_b32_e32 v33, v0
	v_mov_b32_e32 v34, v0
	v_mov_b32_e32 v35, v0
	v_mov_b32_e32 v40, v0
	v_mov_b32_e32 v41, v0
	v_mov_b32_e32 v42, v0
	v_mov_b32_e32 v43, v0
	v_mov_b32_e32 v48, v0
	v_mov_b32_e32 v49, v0
	v_mov_b32_e32 v50, v0
	v_mov_b32_e32 v51, v0
	v_mov_b32_e32 v52, v0
	v_mov_b32_e32 v53, v0
	v_mov_b32_e32 v54, v0
	v_mov_b32_e32 v55, v0
	v_mov_b32_e32 v56, v0
	v_mov_b32_e32 v57, v0
	v_mov_b32_e32 v58, v0
	v_mov_b32_e32 v59, v0
	v_mov_b32_e32 v60, v0
	v_mov_b32_e32 v61, v0
	v_mov_b32_e32 v62, v0
	v_mov_b32_e32 v63, v0
	v_mov_b32_e32 v64, v0
	v_mov_b32_e32 v65, v0
	v_mov_b32_e32 v66, v0
	v_mov_b32_e32 v67, v0
	v_mov_b32_e32 v68, v0
	v_mov_b32_e32 v69, v0
	v_mov_b32_e32 v70, v0
	v_mov_b32_e32 v71, v0
	v_mov_b32_e32 v72, v0
	v_mov_b32_e32 v73, v0
	v_mov_b32_e32 v74, v0
	v_mov_b32_e32 v75, v0
	v_mov_b32_e32 v76, v0
	v_mov_b32_e32 v77, v0
	v_mov_b32_e32 v78, v0
	v_mov_b32_e32 v79, v0
	v_mov_b32_e32 v84, v0
	v_mov_b32_e32 v85, v0
	v_mov_b32_e32 v86, v0
	v_mov_b32_e32 v87, v0
	v_mov_b32_e32 v92, v0
	v_mov_b32_e32 v93, v0
	v_mov_b32_e32 v94, v0
	v_mov_b32_e32 v95, v0
	v_mov_b32_e32 v100, v0
	v_mov_b32_e32 v101, v0
	v_mov_b32_e32 v102, v0
	v_mov_b32_e32 v103, v0
	v_mov_b32_e32 v108, v0
	v_mov_b32_e32 v109, v0
	v_mov_b32_e32 v110, v0
	v_mov_b32_e32 v111, v0
	v_mov_b32_e32 v80, v0
	v_mov_b32_e32 v81, v0
	v_mov_b32_e32 v82, v0
	v_mov_b32_e32 v83, v0
	v_mov_b32_e32 v88, v0
	v_mov_b32_e32 v89, v0
	v_mov_b32_e32 v90, v0
	v_mov_b32_e32 v91, v0
	v_mov_b32_e32 v96, v0
	v_mov_b32_e32 v97, v0
	v_mov_b32_e32 v98, v0
	v_mov_b32_e32 v99, v0
	v_mov_b32_e32 v104, v0
	v_mov_b32_e32 v105, v0
	v_mov_b32_e32 v106, v0
	v_mov_b32_e32 v107, v0
	v_mov_b32_e32 v112, v0
	v_mov_b32_e32 v113, v0
	v_mov_b32_e32 v114, v0
	v_mov_b32_e32 v115, v0
	v_mov_b32_e32 v116, v0
	v_mov_b32_e32 v117, v0
	v_mov_b32_e32 v118, v0
	v_mov_b32_e32 v119, v0
	v_mov_b32_e32 v120, v0
	v_mov_b32_e32 v121, v0
	v_mov_b32_e32 v122, v0
	v_mov_b32_e32 v123, v0
	v_mov_b32_e32 v124, v0
	v_mov_b32_e32 v125, v0
	v_mov_b32_e32 v126, v0
	v_mov_b32_e32 v127, v0
	s_lshr_b32 s80, s3, 8
	s_cmp_lg_u32 s80, 0
	s_cbranch_scc1 .Lprio_1915
	s_setprio 1
